# attention K/V/KPE LDS-DMA: scalar-base + 32-bit lane offset instead of rebuilding 64-bit VGPR addresses per piece
# baseline (speedup 1.0000x reference)
; #define SBAR() __builtin_amdgcn_sched_barrier(0)
; #define DMA_K(t, bf) do { if (ABL & 8) break; const char* kb_ = Kt + (size_t)(t) * KSTEP; LAS unsigned char* kd_ = Kl + (bf) * SHM_K + wid * 1024; \
;     glds16(kb_ + voffK, kd_); glds16(kb_ + 128 + voffK, kd_ + 8192); glds16(Pt + (size_t)(t) * PSTEP + voffP, kd_ + 16384); } while (0)
; #define DMA_V(t, bf) do { if (ABL & 8) break; const char* vb_ = Kt + 256 + (size_t)(t) * KSTEP; LAS unsigned char* vd_ = Vl + (bf) * SHM_V + wid * 1024; \
;     glds16(vb_ + voffV, vd_); glds16(vb_ + (size_t)32 * LDKV * 2 + voffV, vd_ + 8192); } while (0)
; #define END_STEP() do { if (!(ABL & 8)) { asm volatile("s_waitcnt vmcnt(0)" ::: "memory"); __syncthreads(); } } while (0)
; template <int ABL> __device__ __forceinline__ void attn_unit(int b, int h, int qb, const bf16_t* Q, const bf16_t* KV, const bf16_t* KPE, bf16_t* MG, float* ssqa, LAS unsigned char* L) {
;     ...
;     END_STEP(); DMA_K(j + 2, 1); DMA_V(j + 1, 0);
;     SBAR(); QK_TILE(Kl, pA0, pA1, pB0, pB1, alB, true);
.LBB0_759:
	v_lshl_add_u64 v[112:113], s[28:29], 0, v[146:147]
	s_mov_b64 s[54:55], 0x18fc0000
	s_mov_b32 m0, s78
	s_add_u32 s98, s28, s54
	s_addc_u32 s99, s29, s55
	s_waitcnt vmcnt(0)
	s_barrier
	global_load_lds_dwordx4 v146, s[98:99]
	s_add_i32 m0, s78, 0x2000
	s_add_u32 s100, s28, s38
	s_addc_u32 s101, s29, s39
	global_load_lds_dwordx4 v146, s[100:101]
	s_add_i32 m0, s78, 0x4000
	s_add_u32 s98, s28, s40
	s_addc_u32 s99, s29, s41
	global_load_lds_dwordx4 v144, s[98:99]
	s_mov_b32 m0, s58
	s_add_u32 s100, s28, s42
	s_addc_u32 s101, s29, s43
	global_load_lds_dwordx4 v148, s[100:101]
	s_mov_b32 m0, s77
	s_add_u32 s98, s28, s44
	s_addc_u32 s99, s29, s45
	global_load_lds_dwordx4 v148, s[98:99]
	v_exp_f32_e32 v1, v246
	v_exp_f32_e32 v101, v84
	v_exp_f32_e32 v103, v85
	v_exp_f32_e32 v205, v89
	v_exp_f32_e32 v206, v90
	v_sub_f32_e32 v102, v70, v140
	v_sub_f32_e32 v204, v74, v140
	v_exp_f32_e32 v160, v88
	v_sub_f32_e32 v88, v69, v140
	v_sub_f32_e32 v158, v72, v140
	v_exp_f32_e32 v154, v86
	v_exp_f32_e32 v159, v87
	v_exp_f32_e32 v208, v91
	v_exp_f32_e32 v209, v92
	v_exp_f32_e32 v210, v93
	v_exp_f32_e32 v211, v94
	v_sub_f32_e32 v155, v71, v140
	v_sub_f32_e32 v161, v73, v140
	v_sub_f32_e32 v207, v75, v140
	ds_read_b128 v[68:71], v178 offset:32768
	ds_read_b128 v[84:87], v178 offset:36864
	s_waitcnt lgkmcnt(0)
	ds_read_b128 v[104:107], v179 offset:32768
	ds_read_b128 v[108:111], v179 offset:36864
	v_mfma_f32_32x32x16_bf16 v[68:83], v[68:71], v[126:129], 0
	v_cvt_pk_bf16_f32 v100, v1, v101
	v_exp_f32_e32 v226, v99
	v_add_f32_e32 v227, 0, v1
	v_exp_f32_e32 v1, v88
	v_mfma_f32_32x32x16_bf16 v[84:99], v[84:87], v[126:129], 0
	v_add_f32_e32 v228, 0, v101
	v_cvt_pk_bf16_f32 v101, v103, v154
	s_waitcnt lgkmcnt(0)
	ds_read_b128 v[130:133], v177 offset:32768
	ds_read_b128 v[150:153], v177 offset:36864
	v_mfma_f32_32x32x16_bf16 v[68:83], v[104:107], v[122:125], v[68:83]
	v_exp_f32_e32 v229, v102
	v_cvt_pk_bf16_f32 v102, v159, v160
	v_add_f32_e32 v230, 0, v103
	v_mfma_f32_32x32x16_bf16 v[84:99], v[108:111], v[122:125], v[84:99]
	v_add_f32_e32 v105, 0, v154
	v_cvt_pk_bf16_f32 v103, v205, v206
	v_exp_f32_e32 v231, v155
	s_waitcnt lgkmcnt(0)
	ds_read_b128 v[106:109], v176 offset:32768
	ds_read_b128 v[154:157], v176 offset:36864
	v_mfma_f32_32x32x16_bf16 v[68:83], v[130:133], v[118:121], v[68:83]
	v_permlane32_swap_b32_e32 v100, v102
	v_exp_f32_e32 v232, v158
	v_add_f32_e32 v227, v159, v227
	v_mfma_f32_32x32x16_bf16 v[84:99], v[150:153], v[118:121], v[84:99]
	v_permlane32_swap_b32_e32 v101, v103
	v_exp_f32_e32 v233, v161
	v_add_f32_e32 v228, v160, v228
	s_waitcnt lgkmcnt(0)
	ds_read_b128 v[130:133], v178 offset:40960
	ds_read_b128 v[150:153], v178 offset:45056
	v_mfma_f32_32x32x16_bf16 v[68:83], v[106:109], v[114:117], v[68:83]
	v_cvt_pk_bf16_f32 v104, v208, v209
	v_exp_f32_e32 v234, v204
	v_add_f32_e32 v230, v205, v230
	v_mfma_f32_32x32x16_bf16 v[84:99], v[154:157], v[114:117], v[84:99]
	v_add_f32_e32 v236, v206, v105
	v_cvt_pk_bf16_f32 v105, v210, v211
	v_exp_f32_e32 v235, v207
	s_waitcnt lgkmcnt(0)
	ds_read_b128 v[108:111], v179 offset:40960
	ds_read_b128 v[154:157], v179 offset:45056
	v_mfma_f32_32x32x16_bf16 v[68:83], v[130:133], v[238:241], v[68:83]
	v_cvt_pk_bf16_f32 v106, v212, v213
	v_exp_f32_e32 v216, v216
	v_add_f32_e32 v227, v208, v227
	v_mfma_f32_32x32x16_bf16 v[84:99], v[150:153], v[238:241], v[84:99]
	v_cvt_pk_bf16_f32 v107, v214, v215
	v_exp_f32_e32 v217, v217
	v_add_f32_e32 v228, v209, v228
	s_waitcnt lgkmcnt(0)
	ds_read_b128 v[130:133], v177 offset:40960
	ds_read_b128 v[150:153], v177 offset:45056
	v_mfma_f32_32x32x16_bf16 v[68:83], v[108:111], v[242:245], v[68:83]
	v_permlane32_swap_b32_e32 v104, v106
	v_exp_f32_e32 v218, v218
	v_add_f32_e32 v230, v210, v230
	v_mfma_f32_32x32x16_bf16 v[84:99], v[154:157], v[242:245], v[84:99]
	v_add_f32_e32 v111, v211, v236
	v_permlane32_swap_b32_e32 v105, v107
	v_exp_f32_e32 v219, v219
	s_waitcnt lgkmcnt(0)
	ds_read_b128 v[154:157], v176 offset:40960
	ds_read_b128 v[204:207], v176 offset:45056
	v_mfma_f32_32x32x16_bf16 v[68:83], v[130:133], v[248:251], v[68:83]
	v_cvt_pk_bf16_f32 v108, v226, v1
	v_exp_f32_e32 v220, v220
	v_add_f32_e32 v212, v212, v227
	v_mfma_f32_32x32x16_bf16 v[84:99], v[150:153], v[248:251], v[84:99]
	v_cvt_pk_bf16_f32 v109, v229, v231
	v_exp_f32_e32 v221, v221
	v_add_f32_e32 v213, v213, v228
	s_waitcnt lgkmcnt(0)
	ds_read_b128 v[130:133], v178 offset:49152
	ds_read_b128 v[150:153], v178 offset:53248
	ds_read_b128 v[158:161], v171 offset:4096
	v_mfma_f32_32x32x16_bf16 v[68:83], v[154:157], v[252:255], v[68:83]
	v_cvt_pk_bf16_f32 v110, v232, v233
	v_exp_f32_e32 v222, v222
	v_add_f32_e32 v214, v214, v230
	v_mfma_f32_32x32x16_bf16 v[84:99], v[204:207], v[252:255], v[84:99]
	v_add_f32_e32 v215, v215, v111
	v_cvt_pk_bf16_f32 v111, v234, v235
	v_exp_f32_e32 v223, v223
	s_waitcnt lgkmcnt(0)
	ds_read_b128 v[154:157], v179 offset:49152
	ds_read_b128 v[204:207], v179 offset:53248
	ds_read_b128 v[208:211], v170 offset:4096
	v_mfma_f32_32x32x16_bf16 v[68:83], v[130:133], v[158:161], v[68:83]
	v_add_f32_e32 v1, v1, v213
	v_permlane32_swap_b32_e32 v108, v110
	v_add_f32_e32 v226, v226, v212
	v_mfma_f32_32x32x16_bf16 v[84:99], v[150:153], v[158:161], v[84:99]
	v_add_f32_e32 v131, v229, v214
	v_add_f32_e32 v132, v231, v215
	v_permlane32_swap_b32_e32 v109, v111
	s_waitcnt lgkmcnt(0)
	ds_read_b128 v[150:153], v177 offset:49152
	ds_read_b128 v[158:161], v177 offset:53248
	ds_read_b128 v[212:215], v169 offset:4096
	v_mfma_f32_32x32x16_bf16 v[68:83], v[154:157], v[208:211], v[68:83]
	v_add_f32_e32 v133, v232, v226
	v_add_f32_e32 v1, v233, v1
	v_cvt_pk_bf16_f32 v130, v216, v217
	v_mfma_f32_32x32x16_bf16 v[84:99], v[204:207], v[208:211], v[84:99]
	v_add_f32_e32 v226, v234, v131
	v_cvt_pk_bf16_f32 v131, v218, v219
	v_add_f32_e32 v227, v235, v132
	s_waitcnt lgkmcnt(0)
	ds_read_b128 v[154:157], v176 offset:49152
	ds_read_b128 v[204:207], v176 offset:53248
	ds_read_b128 v[208:211], v168 offset:4096
	v_mfma_f32_32x32x16_bf16 v[68:83], v[150:153], v[212:215], v[68:83]
	v_add_f32_e32 v1, v217, v1
	v_cvt_pk_bf16_f32 v132, v220, v221
	v_add_f32_e32 v216, v216, v133
	v_mfma_f32_32x32x16_bf16 v[84:99], v[158:161], v[212:215], v[84:99]
	v_cvt_pk_bf16_f32 v133, v222, v223
	v_add_f32_e32 v150, v218, v226
	v_add_f32_e32 v151, v219, v227
	s_waitcnt lgkmcnt(0)
	v_mfma_f32_32x32x16_bf16 v[68:83], v[154:157], v[208:211], v[68:83]
	v_add_f32_e32 v1, v221, v1
	v_permlane32_swap_b32_e32 v130, v132
	v_add_f32_e32 v152, v220, v216
	v_mfma_f32_32x32x16_bf16 v[84:99], v[204:207], v[208:211], v[84:99]
	v_permlane32_swap_b32_e32 v131, v133
	v_add_f32_e32 v150, v222, v150
	v_add_f32_e32 v151, v223, v151
	v_add_f32_e32 v1, v152, v1
	v_add_f32_e32 v150, v150, v151
	v_add_f32_e32 v205, v1, v150
	v_mov_b32_e32 v206, v205
	s_nop 1
	v_permlane32_swap_b32_e32 v205, v206

; #define DMA_K(t, bf) do { if (ABL & 8) break; const char* kb_ = Kt + (size_t)(t) * KSTEP; LAS unsigned char* kd_ = Kl + (bf) * SHM_K + wid * 1024; \
;     glds16(kb_ + voffK, kd_); glds16(kb_ + 128 + voffK, kd_ + 8192); glds16(Pt + (size_t)(t) * PSTEP + voffP, kd_ + 16384); } while (0)
; #define DMA_V(t, bf) do { if (ABL & 8) break; const char* vb_ = Kt + 256 + (size_t)(t) * KSTEP; LAS unsigned char* vd_ = Vl + (bf) * SHM_V + wid * 1024; \
;     glds16(vb_ + voffV, vd_); glds16(vb_ + (size_t)32 * LDKV * 2 + voffV, vd_ + 8192); } while (0)
; #define END_STEP() do { if (!(ABL & 8)) { asm volatile("s_waitcnt vmcnt(0)" ::: "memory"); __syncthreads(); } } while (0)
; #define RESC(a) do { if (__any((a) < 1.f)) { if (hi == 0) al_l[r32] = (a); asm volatile("s_waitcnt lgkmcnt(0)" ::: "memory"); \
;     _Pragma("unroll") for (int d = 0; d < 4; ++d) _Pragma("unroll") for (int r = 0; r < 16; ++r) o[d][r] *= al_l[crow(r, hi)]; } } while (0)
; template <int ABL> __device__ __forceinline__ void attn_unit(int b, int h, int qb, const bf16_t* Q, const bf16_t* KV, const bf16_t* KPE, bf16_t* MG, float* ssqa, LAS unsigned char* L) {
;     ...
;     RESC(alA);
;     END_STEP(); if (j + 3 < NT) DMA_K(j + 3, 0); DMA_V(j + 2, 1);
.LBB0_764:
	s_waitcnt vmcnt(0)
	v_pk_add_f32 v[130:131], v[84:85], v[140:141] op_sel_hi:[1,0] neg_lo:[0,1] neg_hi:[0,1]
	v_pk_add_f32 v[132:133], v[86:87], v[140:141] op_sel_hi:[1,0] neg_lo:[0,1] neg_hi:[0,1]
	v_pk_add_f32 v[160:161], v[88:89], v[140:141] op_sel_hi:[1,0] neg_lo:[0,1] neg_hi:[0,1]
	v_pk_add_f32 v[158:159], v[90:91], v[140:141] op_sel_hi:[1,0] neg_lo:[0,1] neg_hi:[0,1]
	v_pk_add_f32 v[156:157], v[92:93], v[140:141] op_sel_hi:[1,0] neg_lo:[0,1] neg_hi:[0,1]
	v_pk_add_f32 v[154:155], v[94:95], v[140:141] op_sel_hi:[1,0] neg_lo:[0,1] neg_hi:[0,1]
	v_pk_add_f32 v[152:153], v[96:97], v[140:141] op_sel_hi:[1,0] neg_lo:[0,1] neg_hi:[0,1]
	v_pk_add_f32 v[150:151], v[98:99], v[140:141] op_sel_hi:[1,0] neg_lo:[0,1] neg_hi:[0,1]
	s_cmp_gt_u32 s81, 60
	s_mov_b64 s[54:55], -1
	s_barrier
	s_cbranch_scc1 .LBB0_766
	s_mov_b32 m0, s59
	s_add_u32 s98, s28, s46
	s_addc_u32 s99, s29, s47
	global_load_lds_dwordx4 v146, s[98:99]
	s_mov_b32 m0, s60
	s_add_u32 s100, s28, s48
	s_addc_u32 s101, s29, s49
	global_load_lds_dwordx4 v146, s[100:101]
	s_mov_b32 m0, s61
	s_add_u32 s98, s28, s50
	s_addc_u32 s99, s29, s51
	global_load_lds_dwordx4 v144, s[98:99]
	s_mov_b32 m0, s79
	s_add_u32 s100, s28, s62
	s_addc_u32 s101, s29, s63
	global_load_lds_dwordx4 v148, s[100:101]
	s_mov_b32 m0, s80
	s_add_u32 s98, s28, s64
	s_addc_u32 s99, s29, s65
	global_load_lds_dwordx4 v148, s[98:99]
	v_lshl_add_u64 v[144:145], v[144:145], 0, s[10:11]
	v_lshl_add_u64 v[146:147], v[146:147], 0, s[8:9]
	v_lshl_add_u64 v[148:149], v[148:149], 0, s[8:9]
	s_add_i32 s81, s81, 2
	s_mov_b64 s[54:55], 0

; __global__ void __launch_bounds__(512, 2) hymba_fwd(Args args) {
	.amdhsa_kernel _Z9hymba_fwd4Args
		.amdhsa_group_segment_fixed_size 0
		.amdhsa_private_segment_fixed_size 0
		.amdhsa_kernarg_size 416
		.amdhsa_user_sgpr_count 2
		.amdhsa_user_sgpr_dispatch_ptr 0
		.amdhsa_user_sgpr_queue_ptr 0
		.amdhsa_user_sgpr_kernarg_segment_ptr 1
		.amdhsa_user_sgpr_dispatch_id 0
		.amdhsa_user_sgpr_kernarg_preload_length 0
		.amdhsa_user_sgpr_kernarg_preload_offset 0
		.amdhsa_user_sgpr_private_segment_size 0
		.amdhsa_uses_dynamic_stack 0
		.amdhsa_enable_private_segment 0
		.amdhsa_system_sgpr_workgroup_id_x 1
		.amdhsa_system_sgpr_workgroup_id_y 0
		.amdhsa_system_sgpr_workgroup_id_z 0
		.amdhsa_system_sgpr_workgroup_info 0
		.amdhsa_system_vgpr_workitem_id 0
		.amdhsa_next_free_vgpr 256
		.amdhsa_next_free_sgpr 102
		.amdhsa_accum_offset 256
		.amdhsa_reserve_vcc 1
		.amdhsa_float_round_mode_32 0
		.amdhsa_float_round_mode_16_64 0
		.amdhsa_float_denorm_mode_32 3
		.amdhsa_float_denorm_mode_16_64 3
		.amdhsa_dx10_clamp 1
		.amdhsa_ieee_mode 1
		.amdhsa_fp16_overflow 0
		.amdhsa_tg_split 0
		.amdhsa_exception_fp_ieee_invalid_op 0
		.amdhsa_exception_fp_denorm_src 0
		.amdhsa_exception_fp_ieee_div_zero 0
		.amdhsa_exception_fp_ieee_overflow 0
		.amdhsa_exception_fp_ieee_underflow 0
		.amdhsa_exception_fp_ieee_inexact 0
		.amdhsa_exception_int_div_zero 0
	.end_amdhsa_kernel

; __global__ void __launch_bounds__(512, 2) hymba_fwd(Args args) {
amdhsa.kernels:
  - .agpr_count:     0
    .args:
      - .offset:         0
        .size:           160
        .value_kind:     by_value
      - .offset:         160
        .size:           4
        .value_kind:     hidden_block_count_x
      - .offset:         164
        .size:           4
        .value_kind:     hidden_block_count_y
      - .offset:         168
        .size:           4
        .value_kind:     hidden_block_count_z
      - .offset:         172
        .size:           2
        .value_kind:     hidden_group_size_x
      - .offset:         174
        .size:           2
        .value_kind:     hidden_group_size_y
      - .offset:         176
        .size:           2
        .value_kind:     hidden_group_size_z
      - .offset:         178
        .size:           2
        .value_kind:     hidden_remainder_x
      - .offset:         180
        .size:           2
        .value_kind:     hidden_remainder_y
      - .offset:         182
        .size:           2
        .value_kind:     hidden_remainder_z
      - .offset:         200
        .size:           8
        .value_kind:     hidden_global_offset_x
      - .offset:         208
        .size:           8
        .value_kind:     hidden_global_offset_y
      - .offset:         216
        .size:           8
        .value_kind:     hidden_global_offset_z
      - .offset:         224
        .size:           2
        .value_kind:     hidden_grid_dims
      - .offset:         280
        .size:           4
        .value_kind:     hidden_dynamic_lds_size
    .group_segment_fixed_size: 0
    .kernarg_segment_align: 8
    .kernarg_segment_size: 416
    .language:       OpenCL C
    .language_version:
      - 2
      - 0
    .max_flat_workgroup_size: 512
    .name:           _Z9hymba_fwd4Args
    .private_segment_fixed_size: 0
    .sgpr_count:     108
    .sgpr_spill_count: 44
    .symbol:         _Z9hymba_fwd4Args.kd
    .uniform_work_group_size: 1
    .uses_dynamic_stack: false
    .vgpr_count:     256
    .vgpr_spill_count: 0
    .wavefront_size: 64
